# prep pass 3: rope tables staged in LDS once per phase (ds_read instead of mid-row global loads with vmcnt(0)); row inputs waited for once before the row's first store
# baseline (speedup 1.0000x reference)
.LBB0_1172:
	s_or_b64 exec, exec, s[22:23]
	s_and_saveexec_b64 s[22:23], vcc
	s_cbranch_execz .LBB0_1226
	v_readlane_b32 s4, v254, 29
	v_readlane_b32 s5, v254, 30
	s_lshl_b64 s[2:3], s[4:5], 9
	s_add_u32 s2, s24, s2
	s_addc_u32 s3, s25, s3
	v_lshlrev_b32_e32 v14, 3, v71
	global_load_dwordx2 v[18:19], v14, s[2:3]
	s_lshl_b64 s[2:3], s[4:5], 10
	s_add_u32 s2, s6, s2
	s_addc_u32 s3, s7, s3
	s_lshl_b64 s[4:5], s[4:5], 8
	s_waitcnt lgkmcnt(0)
	s_add_u32 s6, s8, s4
	s_addc_u32 s7, s9, s5
	s_add_u32 s4, s10, s4
	v_lshlrev_b32_e32 v0, 4, v92
	s_addc_u32 s5, s11, s5
	v_and_b32_e32 v0, 0xf0, v0
	global_load_dwordx4 v[2:5], v0, s[4:5]
	global_load_dwordx4 v[6:9], v0, s[6:7]
	global_load_dwordx4 v[10:13], v80, s[2:3]
	v_readlane_b32 s2, v254, 25
	v_readlane_b32 s3, v254, 26
	v_and_b32_e32 v20, 0x70, v74
	s_load_dwordx2 s[2:3], s[2:3], 0x118
	v_lshlrev_b32_e32 v0, 1, v20
	v_lshl_add_u64 v[22:23], s[16:17], 0, v[0:1]
	v_and_b32_e32 v0, 4, v92
	v_cmp_eq_u32_e64 s[10:11], 0, v0
	v_and_b32_e32 v0, 8, v92
	v_cmp_lt_i32_e32 vcc, v207, v206
	v_cmp_eq_u32_e64 s[12:13], 0, v0
	s_waitcnt lgkmcnt(0)
	s_add_u32 s24, s2, 0x5000
	v_cndmask_b32_e32 v0, v204, v207, vcc
	v_cmp_lt_i32_e32 vcc, v208, v206
	v_lshlrev_b32_e32 v68, 2, v0
	s_addc_u32 s25, s3, 0
	v_cndmask_b32_e32 v0, v204, v208, vcc
	v_cmp_lt_i32_e32 vcc, v209, v206
	v_lshlrev_b32_e32 v69, 2, v0
	s_add_u32 s26, s2, 0x6000
	v_cndmask_b32_e32 v0, v204, v209, vcc
	v_cmp_lt_i32_e32 vcc, v220, v206
	v_lshlrev_b32_e32 v75, 2, v0
	v_mov_b32_e32 v79, v1
	v_cndmask_b32_e32 v0, v204, v220, vcc
	v_cmp_lt_i32_e32 vcc, v217, v206
	v_lshlrev_b32_e32 v77, 2, v0
	v_mov_b32_e32 v15, v1
	v_cndmask_b32_e32 v0, v204, v217, vcc
	v_cmp_lt_i32_e32 vcc, v212, v206
	s_addc_u32 s27, s3, 0
	v_lshlrev_b32_e32 v98, 3, v163
	global_load_dwordx2 v[100:101], v98, s[24:25]
	global_load_dwordx2 v[102:103], v98, s[26:27]
	v_add_u32_e32 v99, 0x1000, v98
	global_load_dwordx2 v[104:105], v99, s[26:27]
	s_waitcnt vmcnt(0)
	ds_write_b64 v98, v[100:101]
	ds_write_b64 v98, v[102:103] offset:4096
	ds_write_b64 v98, v[104:105] offset:8192
	s_waitcnt lgkmcnt(0)
	s_barrier
	v_lshlrev_b32_e32 v17, 2, v92
	v_cmp_gt_u32_e64 s[4:5], 16, v71
	v_cmp_gt_u32_e64 s[28:29], 32, v71
	v_cmp_lt_u32_e64 s[6:7], 31, v71
	v_cmp_gt_u32_e64 s[8:9], 8, v71
	v_lshl_add_u64 v[22:23], v[22:23], 0, v[78:79]
	v_lshlrev_b32_e32 v79, 2, v0
	v_cndmask_b32_e32 v0, v204, v212, vcc
	v_lshl_add_u64 v[14:15], s[2:3], 0, v[14:15]
	s_mov_b64 s[2:3], 0xb134000
	v_ashrrev_i32_e32 v71, 31, v70
	v_lshlrev_b32_e32 v80, 2, v0
	v_lshl_add_u64 v[24:25], v[14:15], 0, s[2:3]
	v_lshlrev_b64 v[14:15], 6, v[70:71]
	v_and_b32_e32 v0, 0xe0, v17
	v_lshl_add_u64 v[14:15], v[14:15], 0, v[0:1]
	v_or_b32_e32 v14, v14, v78
	s_mov_b64 s[2:3], 0xcbb4000
	s_movk_i32 s1, 0x300
	v_lshl_add_u64 v[26:27], v[14:15], 0, s[2:3]
	v_mad_i64_i32 v[14:15], s[2:3], v70, s1, 0
	v_lshlrev_b32_e32 v0, 3, v92
	v_or_b32_e32 v14, v14, v72
	s_mov_b64 s[2:3], 0x2134200
	v_and_b32_e32 v0, 0x1f8, v0
	v_lshl_add_u64 v[28:29], v[14:15], 0, s[2:3]
	v_mad_i64_i32 v[14:15], s[2:3], v70, s1, v[0:1]
	v_mov_b32_e32 v73, v1
	s_mov_b64 s[2:3], 0x2134000
	s_movk_i32 s1, 0x740
	v_lshl_add_u64 v[30:31], v[14:15], 0, s[2:3]
	v_mad_i64_i32 v[34:35], s[2:3], v70, s1, 0
	v_mad_i64_i32 v[14:15], s[2:3], v70, s1, v[72:73]
	s_mov_b64 s[2:3], 0x5134200
	s_lshl_b32 s30, s0, 4
	s_mul_i32 s36, s0, 0x3000
	v_lshl_add_u64 v[36:37], v[14:15], 0, s[2:3]
	s_mul_i32 s40, s0, 0x7400
	v_mad_i64_i32 v[14:15], s[0:1], v70, s1, v[0:1]
	v_and_or_b32 v16, v74, 16, v76
	s_ashr_i32 s31, s30, 31
	v_lshlrev_b64 v[32:33], 10, v[70:71]
	s_mov_b64 s[0:1], 0x5134000
	v_and_b32_e32 v21, 12, v17
	s_lshl_b64 s[34:35], s[30:31], 6
	s_mul_hi_i32 s37, s30, 0x300
	v_or_b32_e32 v32, v32, v0
	s_lshl_b64 s[38:39], s[30:31], 10
	s_mul_hi_i32 s41, s30, 0x740
	v_lshl_or_b32 v34, v16, 1, v34
	v_lshl_add_u64 v[38:39], v[14:15], 0, s[0:1]
	s_mov_b64 s[42:43], 0
	v_lshlrev_b32_e32 v40, 1, v16
	s_branch .LBB0_1175

.LBB0_1189:
	s_or_b64 exec, exec, s[46:47]
	s_mov_b64 s[0:1], 0xb134000
	s_waitcnt vmcnt(2)
	v_and_b32_e32 v83, 0xffff0000, v60
	v_and_b32_e32 v65, 0xffff0000, v61
	v_and_b32_e32 v64, s0, v60
	v_lshlrev_b32_e32 v82, 16, v60
	v_mul_f32_e32 v60, v83, v83
	v_lshlrev_b32_e32 v66, 16, v61
	v_mov_b32_e32 v67, v65
	v_pk_fma_f32 v[60:61], v[82:83], v[82:83], v[60:61] op_sel_hi:[1,1,0]
	s_waitcnt vmcnt(1)
	v_lshlrev_b32_e32 v84, 16, v62
	v_and_b32_e32 v85, 0xffff0000, v62
	v_pk_mul_f32 v[64:65], v[64:65], v[64:65]
	v_pk_fma_f32 v[60:61], v[66:67], v[66:67], v[60:61]
	v_pk_mul_f32 v[62:63], v[84:85], v[84:85]
	v_cndmask_b32_e64 v53, v213, v214, s[16:17]
	v_mov_b32_e32 v64, v62
	v_pk_mov_b32 v[60:61], v[62:63], v[60:61] op_sel:[1,0]
	v_lshl_add_u64 v[16:17], v[56:57], 0, s[0:1]
	v_pk_add_f32 v[60:61], v[64:65], v[60:61]
	ds_bpermute_b32 v63, v68, v61
	ds_bpermute_b32 v62, v68, v60
	v_readlane_b32 s0, v254, 29
	v_readlane_b32 s1, v254, 30
	v_readlane_b32 s2, v254, 25
	v_readlane_b32 s3, v254, 26
	s_waitcnt lgkmcnt(0)
	v_pk_add_f32 v[60:61], v[60:61], v[62:63]
	ds_bpermute_b32 v63, v69, v61
	ds_bpermute_b32 v62, v69, v60
	s_load_dwordx2 s[2:3], s[2:3], 0x118
	s_waitcnt lgkmcnt(0)
	v_pk_add_f32 v[60:61], v[60:61], v[62:63]
	ds_bpermute_b32 v63, v75, v61
	ds_bpermute_b32 v62, v75, v60
	s_waitcnt lgkmcnt(0)
	v_pk_add_f32 v[60:61], v[60:61], v[62:63]
	ds_bpermute_b32 v63, v77, v61
	ds_bpermute_b32 v62, v77, v60
	s_waitcnt lgkmcnt(0)
	v_pk_add_f32 v[60:61], v[60:61], v[62:63]
	ds_bpermute_b32 v65, v79, v61
	ds_bpermute_b32 v64, v79, v60
	v_ashrrev_i32_e32 v63, 7, v70
	v_and_b32_e32 v62, v53, v70
	v_and_b32_e32 v53, -2, v63
	v_cndmask_b32_e64 v53, 0, v53, s[16:17]
	s_waitcnt lgkmcnt(0)
	v_pk_add_f32 v[60:61], v[60:61], v[64:65]
	ds_bpermute_b32 v65, v80, v61
	ds_bpermute_b32 v64, v80, v60
	v_add_u32_e32 v86, s0, v53
	s_brev_b32 s0, 60
	s_mov_b32 s1, 0x3b800000
	v_ashrrev_i32_e32 v87, 31, v86
	s_waitcnt lgkmcnt(0)
	v_pk_add_f32 v[60:61], v[60:61], v[64:65]
	v_lshlrev_b64 v[86:87], 8, v[86:87]
	v_pk_fma_f32 v[60:61], v[60:61], s[0:1], v[162:163] op_sel_hi:[1,1,0]
	s_mov_b32 s0, 0x800000
	v_mul_f32_e32 v53, 0x4b800000, v61
	v_cmp_gt_f32_e32 vcc, s0, v61
	v_mov_b32_e32 v63, v1
	v_lshl_add_u64 v[64:65], v[86:87], 0, v[62:63]
	v_cndmask_b32_e32 v53, v61, v53, vcc
	v_rsq_f32_e32 v53, v53
	v_lshl_add_u64 v[86:87], s[2:3], 0, v[30:31]
	v_mul_f32_e32 v61, 0x45800000, v53
	v_cndmask_b32_e32 v78, v53, v61, vcc
	v_mul_f32_e32 v53, 0x4b800000, v60
	v_cmp_gt_f32_e32 vcc, s0, v60
	v_pk_mul_f32 v[82:83], v[78:79], v[82:83] op_sel_hi:[0,1]
	v_pk_mul_f32 v[66:67], v[78:79], v[66:67] op_sel_hi:[0,1]
	v_cndmask_b32_e32 v53, v60, v53, vcc
	v_rsq_f32_e32 v53, v53
	v_pk_mul_f32 v[82:83], v[10:11], v[82:83]
	v_pk_mul_f32 v[66:67], v[12:13], v[66:67]
	v_cvt_pk_bf16_f32 v60, v82, v83
	v_cvt_pk_bf16_f32 v61, v66, v67
	s_waitcnt vmcnt(0)
	global_store_dwordx2 v[86:87], v[60:61], off
	v_mul_f32_e32 v60, 0x45800000, v53
	v_cndmask_b32_e32 v60, v53, v60, vcc
	v_pk_mul_f32 v[60:61], v[60:61], v[84:85] op_sel_hi:[0,1]
	v_pk_mul_f32 v[66:67], v[18:19], v[60:61]
	v_lshl_add_u64 v[60:61], s[2:3], 0, v[28:29]
	v_cvt_pk_bf16_f32 v53, v66, v67
	global_store_dword v[60:61], v53, off
	v_lshlrev_b64 v[60:61], 9, v[64:65]
	s_and_saveexec_b64 s[46:47], s[16:17]
	s_cbranch_execz .LBB0_1191
	v_readlane_b32 s0, v254, 25
	v_readlane_b32 s1, v254, 26
	s_load_dwordx2 s[0:1], s[0:1], 0x110
	v_lshlrev_b32_e32 v82, 2, v74
	v_mov_b32_e32 v83, v1
	s_waitcnt lgkmcnt(0)
	v_lshl_add_u64 v[84:85], s[0:1], 0, v[60:61]
	v_lshl_add_u64 v[82:83], v[84:85], 0, v[82:83]
	v_add_co_u32_e32 v82, vcc, 0x6000000, v82
	s_nop 1
	v_addc_co_u32_e32 v83, vcc, 0, v83, vcc
	global_store_dwordx2 v[82:83], v[66:67], off
.LBB0_1191:
	s_or_b64 exec, exec, s[46:47]
	s_and_saveexec_b64 s[16:17], s[4:5]
	s_cbranch_execz .LBB0_1197
	v_lshlrev_b32_e32 v66, 16, v73
	v_and_b32_e32 v67, 0xffff0000, v73
	s_and_saveexec_b64 s[0:1], s[14:15]
	s_xor_b64 s[46:47], exec, s[0:1]
	s_cbranch_execz .LBB0_1194
	v_and_b32_e32 v53, 63, v70
	v_lshrrev_b32_e32 v63, 6, v62
	v_cndmask_b32_e64 v53, v53, v63, s[8:9]
	v_lshlrev_b32_e32 v63, 3, v76
	v_lshl_or_b32 v53, v53, 6, v63
	ds_read_b64 v[64:65], v53
	s_waitcnt lgkmcnt(0)
	v_pk_mul_f32 v[84:85], v[64:65], v[66:67] op_sel:[1,1] op_sel_hi:[0,1]
	v_pk_mul_f32 v[82:83], v[64:65], v[66:67]
	v_pk_fma_f32 v[66:67], v[64:65], v[66:67], v[84:85] op_sel_hi:[1,0,1]
	s_nop 0
	v_sub_f32_e32 v66, v82, v84

.LBB0_1197:
	s_or_b64 exec, exec, s[16:17]
	v_and_b32_e32 v53, 63, v70
	v_lshrrev_b32_e32 v62, 6, v62
	v_cndmask_b32_e64 v53, v53, v62, s[12:13]
	v_lshlrev_b32_e32 v62, 16, v54
	v_and_b32_e32 v63, 0xffff0000, v54
	v_pk_mul_f32 v[64:65], v[62:63], v[62:63]
	v_lshlrev_b32_e32 v66, 16, v55
	v_and_b32_e32 v67, 0xffff0000, v55
	v_pk_mul_f32 v[54:55], v[66:67], v[66:67]
	v_add_f32_e32 v64, v64, v65
	v_add_f32_e32 v54, v54, v64
	v_add_f32_e32 v54, v55, v54
	ds_bpermute_b32 v55, v80, v54
	s_mov_b32 s0, 0x800000
	v_lshl_or_b32 v53, v53, 4, v21
	v_lshlrev_b32_e32 v53, 3, v53
	s_mov_b64 s[46:47], s[28:29]
	s_waitcnt lgkmcnt(0)
	v_add_f32_e32 v54, v54, v55
	ds_bpermute_b32 v55, v79, v54
	s_waitcnt lgkmcnt(0)
	v_add_f32_e32 v54, v54, v55
	ds_bpermute_b32 v55, v77, v54
	s_waitcnt lgkmcnt(0)
	v_add_f32_e32 v54, v54, v55
	ds_bpermute_b32 v55, v75, v54
	s_waitcnt lgkmcnt(0)
	v_add_f32_e32 v54, v54, v55
	v_fmamk_f32 v54, v54, 0x3c800000, v162
	v_cmp_gt_f32_e32 vcc, s0, v54
	v_mul_f32_e32 v55, 0x4b800000, v54
	s_nop 0
	v_cndmask_b32_e32 v54, v54, v55, vcc
	v_rsq_f32_e32 v54, v54
	s_nop 0
	v_mul_f32_e32 v55, 0x45800000, v54
	v_cndmask_b32_e32 v64, v54, v55, vcc
	v_pk_mul_f32 v[54:55], v[64:65], v[62:63] op_sel_hi:[0,1]
	v_pk_mul_f32 v[62:63], v[64:65], v[66:67] op_sel_hi:[0,1]
	v_pk_mul_f32 v[54:55], v[6:7], v[54:55]
	v_pk_mul_f32 v[62:63], v[8:9], v[62:63]
	s_and_saveexec_b64 s[16:17], s[14:15]
	s_cbranch_execz .LBB0_1199
	ds_read_b128 v[64:67], v53 offset:4112
	ds_read_b128 v[82:85], v53 offset:4096
	ds_bpermute_b32 v86, v77, v54
	ds_bpermute_b32 v87, v77, v55
	ds_bpermute_b32 v88, v77, v62
	ds_bpermute_b32 v89, v77, v63
	s_andn2_b64 s[46:47], s[28:29], exec
	s_waitcnt lgkmcnt(4)
	v_mov_b32_e32 v90, v83
	v_mov_b32_e32 v91, v85
	s_waitcnt lgkmcnt(2)
	v_pk_mul_f32 v[86:87], v[90:91], v[86:87]
	v_mov_b32_e32 v83, v84
	v_cndmask_b32_e64 v85, v87, -v87, s[10:11]
	v_cndmask_b32_e64 v84, v86, -v86, s[10:11]
	v_pk_fma_f32 v[54:55], v[54:55], v[82:83], v[84:85]
	v_mov_b32_e32 v82, v65
	v_mov_b32_e32 v83, v67
	s_waitcnt lgkmcnt(0)
	v_pk_mul_f32 v[82:83], v[82:83], v[88:89]
	v_mov_b32_e32 v65, v66
	v_cndmask_b32_e64 v67, v83, -v83, s[10:11]
	v_cndmask_b32_e64 v66, v82, -v82, s[10:11]
	v_pk_fma_f32 v[62:63], v[62:63], v[64:65], v[66:67]

.LBB0_1205:
	ds_read_b128 v[62:65], v53 offset:4112
	ds_read_b128 v[82:85], v53 offset:4096
	ds_bpermute_b32 v66, v77, v14
	ds_bpermute_b32 v67, v77, v15
	ds_bpermute_b32 v86, v77, v16
	ds_bpermute_b32 v87, v77, v17
	s_waitcnt lgkmcnt(4)
	v_mov_b32_e32 v88, v83
	v_mov_b32_e32 v89, v85
	s_waitcnt lgkmcnt(2)
	v_pk_mul_f32 v[66:67], v[88:89], v[66:67]
	v_mov_b32_e32 v83, v84
	v_cndmask_b32_e64 v67, v67, -v67, s[10:11]
	v_cndmask_b32_e64 v66, v66, -v66, s[10:11]
	v_pk_fma_f32 v[14:15], v[14:15], v[82:83], v[66:67]
	v_mov_b32_e32 v66, v63
	v_mov_b32_e32 v67, v65
	s_waitcnt lgkmcnt(0)
	v_pk_mul_f32 v[66:67], v[66:67], v[86:87]
	v_mov_b32_e32 v63, v64
	v_cndmask_b32_e64 v65, v67, -v67, s[10:11]
	v_cndmask_b32_e64 v64, v66, -v66, s[10:11]
	v_pk_fma_f32 v[16:17], v[16:17], v[62:63], v[64:65]
	s_or_b64 exec, exec, s[16:17]
	s_and_saveexec_b64 s[14:15], s[28:29]
	s_cbranch_execz .LBB0_1202

.LBB0_1210:
	s_or_b64 exec, exec, s[46:47]
	s_and_saveexec_b64 s[46:47], s[4:5]
	s_cbranch_execz .LBB0_1216
	v_and_b32_e32 v57, 0xffff0000, v41
	v_lshlrev_b32_e32 v56, 16, v41
	s_and_saveexec_b64 s[0:1], s[16:17]
	s_xor_b64 s[48:49], exec, s[0:1]
	s_cbranch_execz .LBB0_1213
	v_and_b32_e32 v0, 63, v50
	v_lshrrev_b32_e32 v15, 6, v14
	v_cndmask_b32_e64 v0, v0, v15, s[8:9]
	v_lshlrev_b32_e32 v15, 3, v76
	v_lshl_or_b32 v0, v0, 6, v15
	ds_read_b64 v[16:17], v0
	s_waitcnt lgkmcnt(0)
	v_pk_mul_f32 v[60:61], v[16:17], v[56:57] op_sel:[1,1] op_sel_hi:[0,1]
	v_pk_mul_f32 v[58:59], v[16:17], v[56:57]
	v_pk_fma_f32 v[56:57], v[16:17], v[56:57], v[60:61] op_sel_hi:[1,0,1]
	s_nop 0
	v_sub_f32_e32 v56, v58, v60

.LBB0_1216:
	s_or_b64 exec, exec, s[46:47]
	v_and_b32_e32 v0, 63, v50
	v_lshrrev_b32_e32 v14, 6, v14
	v_cndmask_b32_e64 v0, v0, v14, s[12:13]
	v_lshlrev_b32_e32 v14, 16, v46
	v_and_b32_e32 v15, 0xffff0000, v46
	v_pk_mul_f32 v[16:17], v[14:15], v[14:15]
	v_lshlrev_b32_e32 v56, 16, v47
	v_and_b32_e32 v57, 0xffff0000, v47
	v_lshl_or_b32 v55, v0, 4, v21
	v_pk_mul_f32 v[58:59], v[56:57], v[56:57]
	v_add_f32_e32 v0, v16, v17
	v_add_f32_e32 v0, v58, v0
	v_add_f32_e32 v0, v59, v0
	ds_bpermute_b32 v16, v80, v0
	s_mov_b32 s0, 0x800000
	s_mov_b64 s[48:49], s[28:29]
	s_waitcnt lgkmcnt(0)
	v_add_f32_e32 v0, v0, v16
	ds_bpermute_b32 v16, v79, v0
	s_waitcnt lgkmcnt(0)
	v_add_f32_e32 v0, v0, v16
	ds_bpermute_b32 v16, v77, v0
	s_waitcnt lgkmcnt(0)
	v_add_f32_e32 v0, v0, v16
	ds_bpermute_b32 v16, v75, v0
	s_waitcnt lgkmcnt(0)
	v_add_f32_e32 v0, v0, v16
	v_fmamk_f32 v0, v0, 0x3c800000, v162
	v_cmp_gt_f32_e32 vcc, s0, v0
	v_mul_f32_e32 v16, 0x4b800000, v0
	s_nop 0
	v_cndmask_b32_e32 v0, v0, v16, vcc
	v_rsq_f32_e32 v0, v0
	s_nop 0
	v_mul_f32_e32 v16, 0x45800000, v0
	v_cndmask_b32_e32 v0, v0, v16, vcc
	v_pk_mul_f32 v[14:15], v[0:1], v[14:15] op_sel_hi:[0,1]
	v_pk_mul_f32 v[16:17], v[0:1], v[56:57] op_sel_hi:[0,1]
	v_pk_mul_f32 v[14:15], v[6:7], v[14:15]
	v_pk_mul_f32 v[16:17], v[8:9], v[16:17]
	v_lshlrev_b32_e32 v0, 3, v55
	s_and_saveexec_b64 s[46:47], s[16:17]
	s_cbranch_execz .LBB0_1218
	ds_read_b128 v[56:59], v0 offset:4112
	ds_read_b128 v[60:63], v0 offset:4096
	ds_bpermute_b32 v64, v77, v14
	ds_bpermute_b32 v65, v77, v15
	ds_bpermute_b32 v66, v77, v16
	ds_bpermute_b32 v67, v77, v17
	s_andn2_b64 s[48:49], s[28:29], exec
	s_waitcnt lgkmcnt(4)
	v_mov_b32_e32 v82, v61
	v_mov_b32_e32 v83, v63
	s_waitcnt lgkmcnt(2)
	v_pk_mul_f32 v[64:65], v[82:83], v[64:65]
	v_mov_b32_e32 v61, v62
	v_cndmask_b32_e64 v63, v65, -v65, s[10:11]
	v_cndmask_b32_e64 v62, v64, -v64, s[10:11]
	v_pk_fma_f32 v[14:15], v[14:15], v[60:61], v[62:63]
	v_mov_b32_e32 v60, v57
	v_mov_b32_e32 v61, v59
	s_waitcnt lgkmcnt(0)
	v_pk_mul_f32 v[60:61], v[60:61], v[66:67]
	v_mov_b32_e32 v57, v58
	v_cndmask_b32_e64 v59, v61, -v61, s[10:11]
	v_cndmask_b32_e64 v58, v60, -v60, s[10:11]
	v_pk_fma_f32 v[16:17], v[16:17], v[56:57], v[58:59]

.LBB0_1223:
	ds_read_b128 v[56:59], v0 offset:4112
	ds_read_b128 v[60:63], v0 offset:4096
	ds_bpermute_b32 v64, v77, v14
	ds_bpermute_b32 v65, v77, v15
	ds_bpermute_b32 v66, v77, v16
	ds_bpermute_b32 v67, v77, v17
	s_waitcnt lgkmcnt(4)
	v_mov_b32_e32 v82, v61
	v_mov_b32_e32 v83, v63
	s_waitcnt lgkmcnt(2)
	v_pk_mul_f32 v[64:65], v[82:83], v[64:65]
	v_mov_b32_e32 v61, v62
	v_cndmask_b32_e64 v63, v65, -v65, s[10:11]
	v_cndmask_b32_e64 v62, v64, -v64, s[10:11]
	v_pk_fma_f32 v[14:15], v[14:15], v[60:61], v[62:63]
	v_mov_b32_e32 v60, v57
	v_mov_b32_e32 v61, v59
	s_waitcnt lgkmcnt(0)
	v_pk_mul_f32 v[60:61], v[60:61], v[66:67]
	v_mov_b32_e32 v57, v58
	v_cndmask_b32_e64 v59, v61, -v61, s[10:11]
	v_cndmask_b32_e64 v58, v60, -v60, s[10:11]
	v_pk_fma_f32 v[16:17], v[16:17], v[56:57], v[58:59]
	s_or_b64 exec, exec, s[46:47]
	s_and_saveexec_b64 s[16:17], s[28:29]
	s_cbranch_execz .LBB0_1221
